# v5 (aligned) plus P4 decode-attention units assigned statically, 16 per XCD, instead of first-come from the queue
# speedup vs baseline: 1.0143x; 1.0063x over previous
.LBB0_785:
	s_cmp_lt_i32 s96, 5
	s_cselect_b64 s[4:5], -1, 0
	s_cmp_gt_i32 s97, 4
	s_cselect_b64 s[6:7], -1, 0
	s_and_b64 s[4:5], s[4:5], s[6:7]
	s_andn2_b64 vcc, exec, s[4:5]
	s_cbranch_vccnz .LBB0_1063
	s_lshr_b32 s101, s2, 4
	s_lshl_b32 s101, s101, 3
	s_and_b32 s100, s2, 7
	s_or_b32 s101, s101, s100
	s_bitcmp0_b32 s2, 3
	s_cselect_b32 s100, s101, 0x80
	s_and_b32 s10, s95, 0xffffffc0
	s_bfe_u32 s8, s95, 0x10006
	s_add_u32 s30, s38, 0x12300000
	s_addc_u32 s31, s39, 0
	s_mov_b32 s5, 0
	s_add_u32 s52, s38, 0x100000
	s_mul_i32 s4, s92, 0x60
	s_addc_u32 s53, s39, 0
	s_lshl_b64 s[4:5], s[4:5], 1
	s_add_u32 s56, s30, s4
	s_addc_u32 s57, s31, s5
	s_ashr_i32 s11, s10, 31
	s_lshr_b32 s5, s95, 7
	s_cmpk_lt_u32 s95, 0x80
	s_cselect_b64 s[58:59], -1, 0
	s_lshl_b32 s14, s5, 13
	s_mul_i32 s9, s92, 0x1200
	s_add_i32 s84, 0, 0x22000
	s_mul_i32 s12, s8, 0x1200
	s_add_i32 s83, 0, 0x22900
	s_lshr_b32 s13, s95, 4
	s_and_b32 s15, s14, 0x7fffc000
	s_lshl_b32 s78, s8, 5
	s_add_i32 s45, s84, s9
	s_lshl_b32 s3, s92, 5
	s_add_i32 s76, s83, s12
	s_add_i32 s77, s15, 0
	s_and_b32 s79, s13, 8
	s_or_b32 s80, s78, 8
	s_or_b32 s81, s78, 16
	s_or_b32 s82, s78, 24
	s_add_i32 s83, s83, s9
	s_add_i32 s84, s84, s12
	s_add_u32 s60, s38, 0x10f00000
	s_addc_u32 s61, s39, 0
	s_add_u32 s54, s38, 0x12000000
	s_addc_u32 s55, s39, 0
	s_lshl_b32 s9, s92, 8
	s_add_i32 s88, s9, 0
	v_mbcnt_hi_u32_b32 v187, -1, v254
	s_add_i32 s85, s77, 0x17400
	s_add_i32 s86, s14, 0
	s_add_i32 s87, s88, 0x24400
	s_add_i32 s88, s88, 0x16000
	s_and_b32 s12, 64, s95
	v_writelane_b32 v255, s90, 6
	v_and_b32_e32 v1, 64, v187
	s_cmp_eq_u32 s8, 0
	v_writelane_b32 v255, s91, 7
	s_mul_i32 s4, s92, 0x250
	v_xor_b32_e32 v0, 32, v187
	v_add_u32_e32 v188, 64, v1
	s_cselect_b64 s[8:9], -1, 0
	s_cmp_lg_u32 s12, 0
	v_cmp_lt_i32_e32 vcc, v0, v188
	v_writelane_b32 v255, s95, 8
	s_cselect_b64 s[62:63], -1, 0
	s_add_i32 s90, s4, 0
	s_mul_i32 s4, s92, 0x410
	v_add_u32_e32 v186, s10, v187
	v_cndmask_b32_e32 v0, v187, v0, vcc
	s_lshl_b32 s5, s5, 8
	v_writelane_b32 v255, s92, 5
	s_add_i32 s92, s4, 0
	s_add_i32 s93, 0, 0x21140
	v_lshlrev_b32_e32 v189, 2, v0
	v_cmp_eq_u32_e64 s[6:7], 0, v186
	s_add_i32 s89, s5, 0
	s_lshl_b64 s[64:65], s[10:11], 2
	s_add_i32 s91, s10, 0x200
	s_addk_i32 s92, 0x4c00
	v_mov_b32_e32 v121, 0
	s_mov_b32 s94, 0x8000
	s_movk_i32 s95, 0x600
	s_movk_i32 s96, 0x7fff
	s_movk_i32 s97, 0x50
	s_movk_i32 s50, 0x4000
	s_movk_i32 s51, 0x2000
	s_movk_i32 s4, 0x6000
	s_mov_b32 s5, 0xa000
	s_mov_b32 s48, 0xc000
	s_mov_b32 s49, 0xe000
	s_mov_b32 s74, 0x41000000
	s_lshl_b64 s[66:67], s[10:11], 1
	s_mov_b64 s[68:69], 0x19700400
	s_mov_b32 s75, 0x19700000
	v_mov_b32_e32 v123, s93
	v_mov_b32_e32 v138, 0xff800000
	s_branch .LBB0_789

.LBB0_789:
	s_and_saveexec_b64 s[10:11], s[6:7]
	s_cbranch_execz .LBB0_793
	s_mov_b64 s[14:15], exec
	s_nop 0
	v_mbcnt_lo_u32_b32 v0, s14, 0
	v_mbcnt_hi_u32_b32 v0, s15, v0
	v_cmp_eq_u32_e32 vcc, 0, v0
	s_and_saveexec_b64 s[12:13], vcc
	s_cbranch_execz .LBB0_792
	s_bcnt1_i32_b64 s14, s[14:15]
	v_mov_b32_e32 v1, s14
	s_cmpk_lg_u32 s44, 0x100
	s_cbranch_scc1 .Lmy_deq_dyn
	v_mov_b32_e32 v1, s100
	s_branch .LBB0_792
.Lmy_deq_dyn:
	global_atomic_add v1, v121, v1, s[38:39] offset:256 sc0
.LBB0_792:
	s_or_b64 exec, exec, s[12:13]
	s_waitcnt vmcnt(0)
	v_readfirstlane_b32 s12, v1
	s_movk_i32 s100, 0x80
	v_mov_b32_e32 v1, s93
	s_nop 0
	v_add_u32_e32 v0, s12, v0
	ds_write_b32 v1, v0

.LBB0_1076:
	s_ashr_i32 s29, s28, 31
	s_lshl_b64 s[30:31], s[28:29], 19
	s_add_u32 s30, s3, s30
	s_addc_u32 s31, s45, s31
	s_and_b64 s[40:41], s[6:7], exec
	s_cselect_b32 s29, s31, s53
	s_cselect_b32 s65, s30, s52
	s_ashr_i32 s27, s26, 31
	s_lshl_b64 s[40:41], s[26:27], 19
	s_add_u32 s40, s62, s40
	s_addc_u32 s41, s63, s41
	s_and_b64 s[46:47], s[6:7], exec
	s_cselect_b32 s27, s41, s55
	s_cselect_b32 s66, s40, s54
	s_add_u32 s52, s52, 0x40080
	s_addc_u32 s53, s53, 0
	s_add_u32 s67, s54, 0x100
	v_mov_b32_e32 v0, 0
	s_addc_u32 s68, s55, 0
	s_mov_b32 s69, -2
	v_mov_b32_e32 v1, v0
	v_mov_b32_e32 v2, v0
	v_mov_b32_e32 v3, v0
	v_mov_b32_e32 v4, v0
	v_mov_b32_e32 v5, v0
	v_mov_b32_e32 v6, v0
	v_mov_b32_e32 v7, v0
	v_mov_b32_e32 v16, v0
	v_mov_b32_e32 v17, v0
	v_mov_b32_e32 v18, v0
	v_mov_b32_e32 v19, v0
	v_mov_b32_e32 v20, v0
	v_mov_b32_e32 v21, v0
	v_mov_b32_e32 v22, v0
	v_mov_b32_e32 v23, v0
	v_mov_b32_e32 v32, v0
	v_mov_b32_e32 v33, v0
	v_mov_b32_e32 v34, v0
	v_mov_b32_e32 v35, v0
	v_mov_b32_e32 v36, v0
	v_mov_b32_e32 v37, v0
	v_mov_b32_e32 v38, v0
	v_mov_b32_e32 v39, v0
	v_mov_b32_e32 v48, v0
	v_mov_b32_e32 v49, v0
	v_mov_b32_e32 v50, v0
	v_mov_b32_e32 v51, v0
	v_mov_b32_e32 v52, v0
	v_mov_b32_e32 v53, v0
	v_mov_b32_e32 v54, v0
	v_mov_b32_e32 v55, v0
	v_mov_b32_e32 v8, v0
	v_mov_b32_e32 v9, v0
	v_mov_b32_e32 v10, v0
	v_mov_b32_e32 v11, v0
	v_mov_b32_e32 v12, v0
	v_mov_b32_e32 v13, v0
	v_mov_b32_e32 v14, v0
	v_mov_b32_e32 v15, v0
	v_mov_b32_e32 v24, v0
	v_mov_b32_e32 v25, v0
	v_mov_b32_e32 v26, v0
	v_mov_b32_e32 v27, v0
	v_mov_b32_e32 v28, v0
	v_mov_b32_e32 v29, v0
	v_mov_b32_e32 v30, v0
	v_mov_b32_e32 v31, v0
	v_mov_b32_e32 v40, v0
	v_mov_b32_e32 v41, v0
	v_mov_b32_e32 v42, v0
	v_mov_b32_e32 v43, v0
	v_mov_b32_e32 v44, v0
	v_mov_b32_e32 v45, v0
	v_mov_b32_e32 v46, v0
	v_mov_b32_e32 v47, v0
	v_mov_b32_e32 v56, v0
	v_mov_b32_e32 v57, v0
	v_mov_b32_e32 v58, v0
	v_mov_b32_e32 v59, v0
	v_mov_b32_e32 v60, v0
	v_mov_b32_e32 v61, v0
	v_mov_b32_e32 v62, v0
	v_mov_b32_e32 v63, v0
	v_mov_b32_e32 v64, v0
	v_mov_b32_e32 v65, v0
	v_mov_b32_e32 v66, v0
	v_mov_b32_e32 v67, v0
	v_mov_b32_e32 v68, v0
	v_mov_b32_e32 v69, v0
	v_mov_b32_e32 v70, v0
	v_mov_b32_e32 v71, v0
	v_mov_b32_e32 v80, v0
	v_mov_b32_e32 v81, v0
	v_mov_b32_e32 v82, v0
	v_mov_b32_e32 v83, v0
	v_mov_b32_e32 v84, v0
	v_mov_b32_e32 v85, v0
	v_mov_b32_e32 v86, v0
	v_mov_b32_e32 v87, v0
	v_mov_b32_e32 v96, v0
	v_mov_b32_e32 v97, v0
	v_mov_b32_e32 v98, v0
	v_mov_b32_e32 v99, v0
	v_mov_b32_e32 v100, v0
	v_mov_b32_e32 v101, v0
	v_mov_b32_e32 v102, v0
	v_mov_b32_e32 v103, v0
	v_mov_b32_e32 v112, v0
	v_mov_b32_e32 v113, v0
	v_mov_b32_e32 v114, v0
	v_mov_b32_e32 v115, v0
	v_mov_b32_e32 v116, v0
	v_mov_b32_e32 v117, v0
	v_mov_b32_e32 v118, v0
	v_mov_b32_e32 v119, v0
	v_mov_b32_e32 v72, v0
	v_mov_b32_e32 v73, v0
	v_mov_b32_e32 v74, v0
	v_mov_b32_e32 v75, v0
	v_mov_b32_e32 v76, v0
	v_mov_b32_e32 v77, v0
	v_mov_b32_e32 v78, v0
	v_mov_b32_e32 v79, v0
	v_mov_b32_e32 v88, v0
	v_mov_b32_e32 v89, v0
	v_mov_b32_e32 v90, v0
	v_mov_b32_e32 v91, v0
	v_mov_b32_e32 v92, v0
	v_mov_b32_e32 v93, v0
	v_mov_b32_e32 v94, v0
	v_mov_b32_e32 v95, v0
	v_mov_b32_e32 v104, v0
	v_mov_b32_e32 v105, v0
	v_mov_b32_e32 v106, v0
	v_mov_b32_e32 v107, v0
	v_mov_b32_e32 v108, v0
	v_mov_b32_e32 v109, v0
	v_mov_b32_e32 v110, v0
	v_mov_b32_e32 v111, v0
	v_mov_b32_e32 v120, v0
	v_mov_b32_e32 v121, v0
	v_mov_b32_e32 v122, v0
	v_mov_b32_e32 v123, v0
	v_mov_b32_e32 v124, v0
	v_mov_b32_e32 v125, v0
	v_mov_b32_e32 v126, v0
	v_mov_b32_e32 v127, v0
	s_nop 0
	s_nop 0
.LBB0_1077:
	ds_read_b128 v[144:147], v154
	ds_read_b128 v[158:161], v154 offset:1024
	ds_read_b128 v[162:165], v154 offset:2048
	ds_read_b128 v[166:169], v154 offset:3072
	ds_read_b128 v[170:173], v155
	ds_read_b128 v[174:177], v155 offset:1024
	ds_read_b128 v[178:181], v155 offset:2048
	ds_read_b128 v[182:185], v155 offset:3072
	s_add_u32 s46, s52, 0xfffc0080
	s_addc_u32 s47, s53, -1
	s_cmp_eq_u32 s69, 12
	s_cselect_b32 s57, s29, s47
	s_cselect_b32 s56, s65, s46
	s_cselect_b32 s55, s27, s68
	s_cselect_b32 s54, s66, s67
	v_lshl_add_u64 v[148:149], s[52:53], 0, v[136:137]
	s_add_i32 m0, s43, 0xc000
	ds_read_b128 v[186:189], v156
	ds_read_b128 v[190:193], v156 offset:1024
	ds_read_b128 v[198:201], v156 offset:2048
	ds_read_b128 v[202:205], v156 offset:3072
	ds_read_b128 v[206:209], v156 offset:4096
	ds_read_b128 v[210:213], v156 offset:5120
	ds_read_b128 v[214:217], v156 offset:6144
	ds_read_b128 v[218:221], v156 offset:7168
	global_load_lds_dwordx4 v[148:149], off
	v_lshl_add_u64 v[148:149], s[52:53], 0, v[138:139]
	s_add_i32 m0, s43, 0xe000
	s_nop 0
	global_load_lds_dwordx4 v[148:149], off
	s_waitcnt vmcnt(8)
	s_waitcnt lgkmcnt(0)
	s_barrier
	s_setprio 1
	s_waitcnt lgkmcnt(0)
	v_mfma_f32_16x16x32_bf16 v[124:127], v[144:147], v[186:189], v[124:127]
	v_mfma_f32_16x16x32_bf16 v[120:123], v[162:165], v[186:189], v[120:123]
	v_mfma_f32_16x16x32_bf16 v[108:111], v[144:147], v[198:201], v[108:111]
	v_mfma_f32_16x16x32_bf16 v[104:107], v[162:165], v[198:201], v[104:107]
	v_mfma_f32_16x16x32_bf16 v[92:95], v[144:147], v[206:209], v[92:95]
	v_mfma_f32_16x16x32_bf16 v[88:91], v[162:165], v[206:209], v[88:91]
	v_mfma_f32_16x16x32_bf16 v[76:79], v[144:147], v[214:217], v[76:79]
	v_mfma_f32_16x16x32_bf16 v[72:75], v[162:165], v[214:217], v[72:75]
	v_mfma_f32_16x16x32_bf16 v[124:127], v[158:161], v[190:193], v[124:127]
	v_mfma_f32_16x16x32_bf16 v[120:123], v[166:169], v[190:193], v[120:123]
	v_mfma_f32_16x16x32_bf16 v[108:111], v[158:161], v[202:205], v[108:111]
	v_mfma_f32_16x16x32_bf16 v[104:107], v[166:169], v[202:205], v[104:107]
	v_mfma_f32_16x16x32_bf16 v[92:95], v[158:161], v[210:213], v[92:95]
	v_mfma_f32_16x16x32_bf16 v[88:91], v[166:169], v[210:213], v[88:91]
	v_mfma_f32_16x16x32_bf16 v[76:79], v[158:161], v[218:221], v[76:79]
	v_mfma_f32_16x16x32_bf16 v[72:75], v[166:169], v[218:221], v[72:75]
	s_setprio 0
	s_setprio 1
	v_mfma_f32_16x16x32_bf16 v[116:119], v[170:173], v[186:189], v[116:119]
	v_mfma_f32_16x16x32_bf16 v[112:115], v[178:181], v[186:189], v[112:115]
	v_mfma_f32_16x16x32_bf16 v[100:103], v[170:173], v[198:201], v[100:103]
	v_mfma_f32_16x16x32_bf16 v[96:99], v[178:181], v[198:201], v[96:99]
	v_mfma_f32_16x16x32_bf16 v[84:87], v[170:173], v[206:209], v[84:87]
	v_mfma_f32_16x16x32_bf16 v[80:83], v[178:181], v[206:209], v[80:83]
	v_mfma_f32_16x16x32_bf16 v[68:71], v[170:173], v[214:217], v[68:71]
	v_mfma_f32_16x16x32_bf16 v[64:67], v[178:181], v[214:217], v[64:67]
	v_mfma_f32_16x16x32_bf16 v[116:119], v[174:177], v[190:193], v[116:119]
	v_mfma_f32_16x16x32_bf16 v[112:115], v[182:185], v[190:193], v[112:115]
	v_mfma_f32_16x16x32_bf16 v[100:103], v[174:177], v[202:205], v[100:103]
	v_mfma_f32_16x16x32_bf16 v[96:99], v[182:185], v[202:205], v[96:99]
	v_mfma_f32_16x16x32_bf16 v[84:87], v[174:177], v[210:213], v[84:87]
	v_mfma_f32_16x16x32_bf16 v[80:83], v[182:185], v[210:213], v[80:83]
	v_mfma_f32_16x16x32_bf16 v[68:71], v[174:177], v[218:221], v[68:71]
	v_mfma_f32_16x16x32_bf16 v[64:67], v[182:185], v[218:221], v[64:67]
	s_setprio 0
	s_barrier
	s_add_i32 s46, s61, s4
	v_lshl_add_u64 v[148:149], s[54:55], 0, v[132:133]
	s_mov_b32 m0, s46
	ds_read_b128 v[186:189], v156 offset:16384
	ds_read_b128 v[190:193], v156 offset:17408
	ds_read_b128 v[198:201], v156 offset:18432
	ds_read_b128 v[202:205], v156 offset:19456
	ds_read_b128 v[206:209], v156 offset:20480
	ds_read_b128 v[210:213], v156 offset:21504
	ds_read_b128 v[214:217], v156 offset:22528
	ds_read_b128 v[218:221], v156 offset:23552
	global_load_lds_dwordx4 v[148:149], off
	s_add_i32 m0, s46, 0x2000
	s_add_u32 s46, s54, 0x40000
	v_lshl_add_u64 v[194:195], s[54:55], 0, v[128:129]
	s_addc_u32 s47, s55, 0
	s_add_i32 s70, s64, s4
	global_load_lds_dwordx4 v[194:195], off
	v_lshl_add_u64 v[196:197], s[46:47], 0, v[132:133]
	s_mov_b32 m0, s70
	v_lshl_add_u64 v[222:223], s[56:57], 0, v[130:131]
	global_load_lds_dwordx4 v[196:197], off
	v_lshl_add_u64 v[196:197], s[46:47], 0, v[128:129]
	s_add_i32 m0, s70, 0x2000
	s_nop 0
	global_load_lds_dwordx4 v[196:197], off
	v_lshl_add_u64 v[196:197], s[56:57], 0, v[134:135]
	s_mov_b32 m0, s43
	s_nop 0
	global_load_lds_dwordx4 v[196:197], off
	s_mov_b32 m0, s48
	s_nop 0
	global_load_lds_dwordx4 v[222:223], off
	s_nop 0
	s_waitcnt vmcnt(8)
	s_waitcnt lgkmcnt(0)
	s_barrier
	s_setprio 1
	s_waitcnt lgkmcnt(0)
	v_mfma_f32_16x16x32_bf16 v[60:63], v[144:147], v[186:189], v[60:63]
	v_mfma_f32_16x16x32_bf16 v[56:59], v[162:165], v[186:189], v[56:59]
	v_mfma_f32_16x16x32_bf16 v[44:47], v[144:147], v[198:201], v[44:47]
	v_mfma_f32_16x16x32_bf16 v[40:43], v[162:165], v[198:201], v[40:43]
	v_mfma_f32_16x16x32_bf16 v[28:31], v[144:147], v[206:209], v[28:31]
	v_mfma_f32_16x16x32_bf16 v[24:27], v[162:165], v[206:209], v[24:27]
	v_mfma_f32_16x16x32_bf16 v[12:15], v[144:147], v[214:217], v[12:15]
	v_mfma_f32_16x16x32_bf16 v[8:11], v[162:165], v[214:217], v[8:11]
	v_mfma_f32_16x16x32_bf16 v[60:63], v[158:161], v[190:193], v[60:63]
	v_mfma_f32_16x16x32_bf16 v[56:59], v[166:169], v[190:193], v[56:59]
	v_mfma_f32_16x16x32_bf16 v[44:47], v[158:161], v[202:205], v[44:47]
	v_mfma_f32_16x16x32_bf16 v[40:43], v[166:169], v[202:205], v[40:43]
	v_mfma_f32_16x16x32_bf16 v[28:31], v[158:161], v[210:213], v[28:31]
	v_mfma_f32_16x16x32_bf16 v[24:27], v[166:169], v[210:213], v[24:27]
	v_mfma_f32_16x16x32_bf16 v[12:15], v[158:161], v[218:221], v[12:15]
	v_mfma_f32_16x16x32_bf16 v[8:11], v[166:169], v[218:221], v[8:11]
	s_setprio 0
	s_setprio 1
	v_mfma_f32_16x16x32_bf16 v[52:55], v[170:173], v[186:189], v[52:55]
	v_mfma_f32_16x16x32_bf16 v[48:51], v[178:181], v[186:189], v[48:51]
	v_mfma_f32_16x16x32_bf16 v[36:39], v[170:173], v[198:201], v[36:39]
	v_mfma_f32_16x16x32_bf16 v[32:35], v[178:181], v[198:201], v[32:35]
	v_mfma_f32_16x16x32_bf16 v[20:23], v[170:173], v[206:209], v[20:23]
	v_mfma_f32_16x16x32_bf16 v[16:19], v[178:181], v[206:209], v[16:19]
	v_mfma_f32_16x16x32_bf16 v[4:7], v[170:173], v[214:217], v[4:7]
	v_mfma_f32_16x16x32_bf16 v[0:3], v[178:181], v[214:217], v[0:3]
	v_mfma_f32_16x16x32_bf16 v[52:55], v[174:177], v[190:193], v[52:55]
	v_mfma_f32_16x16x32_bf16 v[48:51], v[182:185], v[190:193], v[48:51]
	v_mfma_f32_16x16x32_bf16 v[36:39], v[174:177], v[202:205], v[36:39]
	v_mfma_f32_16x16x32_bf16 v[32:35], v[182:185], v[202:205], v[32:35]
	v_mfma_f32_16x16x32_bf16 v[20:23], v[174:177], v[210:213], v[20:23]
	v_mfma_f32_16x16x32_bf16 v[16:19], v[182:185], v[210:213], v[16:19]
	v_mfma_f32_16x16x32_bf16 v[4:7], v[174:177], v[218:221], v[4:7]
	v_mfma_f32_16x16x32_bf16 v[0:3], v[182:185], v[218:221], v[0:3]
	s_setprio 0
	s_barrier
	s_add_i32 s70, 0, 0x18000
	v_add_u32_e32 v157, s70, v152
	s_add_i32 s71, 0, 0x1c000
	ds_read_b128 v[144:147], v157
	ds_read_b128 v[158:161], v157 offset:1024
	ds_read_b128 v[162:165], v157 offset:2048
	ds_read_b128 v[166:169], v157 offset:3072
	v_add_u32_e32 v157, s71, v152
	ds_read_b128 v[170:173], v157
	ds_read_b128 v[174:177], v157 offset:1024
	ds_read_b128 v[178:181], v157 offset:2048
	ds_read_b128 v[182:185], v157 offset:3072
	s_add_u32 s46, s56, 0x40000
	s_addc_u32 s47, s57, 0
	s_mov_b32 m0, s49
	v_lshl_add_u64 v[224:225], s[46:47], 0, v[134:135]
	ds_read_b128 v[186:189], v156 offset:32768
	ds_read_b128 v[190:193], v156 offset:33792
	ds_read_b128 v[198:201], v156 offset:34816
	ds_read_b128 v[202:205], v156 offset:35840
	ds_read_b128 v[206:209], v156 offset:36864
	ds_read_b128 v[210:213], v156 offset:37888
	ds_read_b128 v[214:217], v156 offset:38912
	ds_read_b128 v[218:221], v156 offset:39936
	global_load_lds_dwordx4 v[224:225], off
	v_lshl_add_u64 v[224:225], s[46:47], 0, v[130:131]
	s_mov_b32 m0, s50
	s_nop 0
	global_load_lds_dwordx4 v[224:225], off
	s_nop 0
	s_waitcnt vmcnt(8)
	s_waitcnt lgkmcnt(0)
	s_barrier
	s_setprio 1
	s_waitcnt lgkmcnt(0)
	v_mfma_f32_16x16x32_bf16 v[124:127], v[144:147], v[186:189], v[124:127]
	v_mfma_f32_16x16x32_bf16 v[120:123], v[162:165], v[186:189], v[120:123]
	v_mfma_f32_16x16x32_bf16 v[108:111], v[144:147], v[198:201], v[108:111]
	v_mfma_f32_16x16x32_bf16 v[104:107], v[162:165], v[198:201], v[104:107]
	v_mfma_f32_16x16x32_bf16 v[92:95], v[144:147], v[206:209], v[92:95]
	v_mfma_f32_16x16x32_bf16 v[88:91], v[162:165], v[206:209], v[88:91]
	v_mfma_f32_16x16x32_bf16 v[76:79], v[144:147], v[214:217], v[76:79]
	v_mfma_f32_16x16x32_bf16 v[72:75], v[162:165], v[214:217], v[72:75]
	v_mfma_f32_16x16x32_bf16 v[124:127], v[158:161], v[190:193], v[124:127]
	v_mfma_f32_16x16x32_bf16 v[120:123], v[166:169], v[190:193], v[120:123]
	v_mfma_f32_16x16x32_bf16 v[108:111], v[158:161], v[202:205], v[108:111]
	v_mfma_f32_16x16x32_bf16 v[104:107], v[166:169], v[202:205], v[104:107]
	v_mfma_f32_16x16x32_bf16 v[92:95], v[158:161], v[210:213], v[92:95]
	v_mfma_f32_16x16x32_bf16 v[88:91], v[166:169], v[210:213], v[88:91]
	v_mfma_f32_16x16x32_bf16 v[76:79], v[158:161], v[218:221], v[76:79]
	v_mfma_f32_16x16x32_bf16 v[72:75], v[166:169], v[218:221], v[72:75]
	s_setprio 0
	s_setprio 1
	v_mfma_f32_16x16x32_bf16 v[116:119], v[170:173], v[186:189], v[116:119]
	v_mfma_f32_16x16x32_bf16 v[112:115], v[178:181], v[186:189], v[112:115]
	v_mfma_f32_16x16x32_bf16 v[100:103], v[170:173], v[198:201], v[100:103]
	v_mfma_f32_16x16x32_bf16 v[96:99], v[178:181], v[198:201], v[96:99]
	v_mfma_f32_16x16x32_bf16 v[84:87], v[170:173], v[206:209], v[84:87]
	v_mfma_f32_16x16x32_bf16 v[80:83], v[178:181], v[206:209], v[80:83]
	v_mfma_f32_16x16x32_bf16 v[68:71], v[170:173], v[214:217], v[68:71]
	v_mfma_f32_16x16x32_bf16 v[64:67], v[178:181], v[214:217], v[64:67]
	v_mfma_f32_16x16x32_bf16 v[116:119], v[174:177], v[190:193], v[116:119]
	v_mfma_f32_16x16x32_bf16 v[112:115], v[182:185], v[190:193], v[112:115]
	v_mfma_f32_16x16x32_bf16 v[100:103], v[174:177], v[202:205], v[100:103]
	v_mfma_f32_16x16x32_bf16 v[96:99], v[182:185], v[202:205], v[96:99]
	v_mfma_f32_16x16x32_bf16 v[84:87], v[174:177], v[210:213], v[84:87]
	v_mfma_f32_16x16x32_bf16 v[80:83], v[182:185], v[210:213], v[80:83]
	v_mfma_f32_16x16x32_bf16 v[68:71], v[174:177], v[218:221], v[68:71]
	v_mfma_f32_16x16x32_bf16 v[64:67], v[182:185], v[218:221], v[64:67]
	s_setprio 0
	s_barrier
	s_add_i32 s46, s70, s4
	v_lshl_add_u64 v[148:149], v[148:149], 0, s[16:17]
	s_mov_b32 m0, s46
	ds_read_b128 v[186:189], v156 offset:49152
	ds_read_b128 v[190:193], v156 offset:50176
	ds_read_b128 v[198:201], v156 offset:51200
	ds_read_b128 v[202:205], v156 offset:52224
	ds_read_b128 v[206:209], v156 offset:53248
	ds_read_b128 v[210:213], v156 offset:54272
	ds_read_b128 v[214:217], v156 offset:55296
	ds_read_b128 v[218:221], v156 offset:56320
	global_load_lds_dwordx4 v[148:149], off
	s_add_i32 m0, s46, 0x2000
	s_add_u32 s46, s54, 0x40080
	v_lshl_add_u64 v[148:149], v[194:195], 0, s[16:17]
	s_addc_u32 s47, s55, 0
	s_add_i32 s54, s71, s4
	global_load_lds_dwordx4 v[148:149], off
	v_lshl_add_u64 v[148:149], s[46:47], 0, v[132:133]
	s_mov_b32 m0, s54
	s_nop 0
	global_load_lds_dwordx4 v[148:149], off
	v_lshl_add_u64 v[148:149], s[46:47], 0, v[128:129]
	s_add_i32 m0, s54, 0x2000
	s_nop 0
	global_load_lds_dwordx4 v[148:149], off
	v_lshl_add_u64 v[148:149], v[196:197], 0, s[16:17]
	s_mov_b32 m0, s58
	s_nop 0
	global_load_lds_dwordx4 v[148:149], off
	v_lshl_add_u64 v[148:149], v[222:223], 0, s[16:17]
	s_mov_b32 m0, s59
	s_nop 0
	global_load_lds_dwordx4 v[148:149], off
	s_waitcnt vmcnt(8)
	s_waitcnt lgkmcnt(0)
	s_barrier
	s_setprio 1
	s_waitcnt lgkmcnt(0)
	v_mfma_f32_16x16x32_bf16 v[60:63], v[144:147], v[186:189], v[60:63]
	v_mfma_f32_16x16x32_bf16 v[56:59], v[162:165], v[186:189], v[56:59]
	v_mfma_f32_16x16x32_bf16 v[44:47], v[144:147], v[198:201], v[44:47]
	v_mfma_f32_16x16x32_bf16 v[40:43], v[162:165], v[198:201], v[40:43]
	v_mfma_f32_16x16x32_bf16 v[28:31], v[144:147], v[206:209], v[28:31]
	v_mfma_f32_16x16x32_bf16 v[24:27], v[162:165], v[206:209], v[24:27]
	v_mfma_f32_16x16x32_bf16 v[12:15], v[144:147], v[214:217], v[12:15]
	v_mfma_f32_16x16x32_bf16 v[8:11], v[162:165], v[214:217], v[8:11]
	v_mfma_f32_16x16x32_bf16 v[60:63], v[158:161], v[190:193], v[60:63]
	v_mfma_f32_16x16x32_bf16 v[56:59], v[166:169], v[190:193], v[56:59]
	v_mfma_f32_16x16x32_bf16 v[44:47], v[158:161], v[202:205], v[44:47]
	v_mfma_f32_16x16x32_bf16 v[40:43], v[166:169], v[202:205], v[40:43]
	v_mfma_f32_16x16x32_bf16 v[28:31], v[158:161], v[210:213], v[28:31]
	v_mfma_f32_16x16x32_bf16 v[24:27], v[166:169], v[210:213], v[24:27]
	v_mfma_f32_16x16x32_bf16 v[12:15], v[158:161], v[218:221], v[12:15]
	v_mfma_f32_16x16x32_bf16 v[8:11], v[166:169], v[218:221], v[8:11]
	s_setprio 0
	s_setprio 1
	v_mfma_f32_16x16x32_bf16 v[52:55], v[170:173], v[186:189], v[52:55]
	v_mfma_f32_16x16x32_bf16 v[48:51], v[178:181], v[186:189], v[48:51]
	v_mfma_f32_16x16x32_bf16 v[36:39], v[170:173], v[198:201], v[36:39]
	v_mfma_f32_16x16x32_bf16 v[32:35], v[178:181], v[198:201], v[32:35]
	v_mfma_f32_16x16x32_bf16 v[20:23], v[170:173], v[206:209], v[20:23]
	v_mfma_f32_16x16x32_bf16 v[16:19], v[178:181], v[206:209], v[16:19]
	v_mfma_f32_16x16x32_bf16 v[4:7], v[170:173], v[214:217], v[4:7]
	v_mfma_f32_16x16x32_bf16 v[0:3], v[178:181], v[214:217], v[0:3]
	v_mfma_f32_16x16x32_bf16 v[52:55], v[174:177], v[190:193], v[52:55]
	v_mfma_f32_16x16x32_bf16 v[48:51], v[182:185], v[190:193], v[48:51]
	v_mfma_f32_16x16x32_bf16 v[36:39], v[174:177], v[202:205], v[36:39]
	v_mfma_f32_16x16x32_bf16 v[32:35], v[182:185], v[202:205], v[32:35]
	v_mfma_f32_16x16x32_bf16 v[20:23], v[174:177], v[210:213], v[20:23]
	v_mfma_f32_16x16x32_bf16 v[16:19], v[182:185], v[210:213], v[16:19]
	v_mfma_f32_16x16x32_bf16 v[4:7], v[174:177], v[218:221], v[4:7]
	v_mfma_f32_16x16x32_bf16 v[0:3], v[182:185], v[218:221], v[0:3]
	s_setprio 0
	s_barrier
	s_add_i32 s69, s69, 2
	s_add_u32 s52, s52, 0x100
	s_addc_u32 s53, s53, 0
	s_add_u32 s67, s67, 0x100
	s_addc_u32 s68, s68, 0
	s_cmp_gt_u32 s69, 13
	s_cbranch_scc0 .LBB0_1077
	s_and_b64 vcc, exec, s[18:19]
	s_cbranch_vccz .LBB0_1080
	s_barrier
